# layer-1 input rmsnorm and final rmsnorm loops software-pipelined (next row in flight) now that their rows are XCD-local
# baseline (speedup 1.0000x reference)
; DI int otid() { int t = threadIdx.x; asm volatile("" : "+v"(t)); return t; }
; DI void rmsnorm_phase(const float* __restrict__ X, const float* __restrict__ g, bf16_t* __restrict__ H, float* __restrict__ OF) {
;   const int tid = otid(), lane = tid & 63;
;   const int gw = blockIdx.x * NWV + (tid >> 6), nw = gridDim.x * NWV;
;   for (int row = gw; row < T; row += nw) {
;     const float* xr = X + (size_t)row * D;
;     f32x4 v[8];
;     float ss = 0.f;
; #pragma unroll
;     for (int i = 0; i < 8; ++i) { v[i] = *(const f32x4*)(xr + lane * 4 + 256 * i); ss += v[i][0] * v[i][0] + v[i][1] * v[i][1] + v[i][2] * v[i][2] + v[i][3] * v[i][3]; }
;     ss = wave_sum(ss);
;     const float rstd = rsqrtf(ss * (1.f / D) + EPS);
; #pragma unroll
;     for (int i = 0; i < 8; ++i) {
;       const f32x4 gg = *(const f32x4*)(g + lane * 4 + 256 * i);
.Lxr_0:
	s_movk_i32 s0, 0x4000
	v_cmp_gt_i32_e32 vcc, s0, v48
	s_and_saveexec_b64 s[0:1], vcc
	s_cbranch_execz .LBB0_822
	v_lshlrev_b32_e32 v0, 4, v32
	v_and_b32_e32 v0, 0x3f0, v0
	v_mov_b32_e32 v1, 0
	v_lshl_add_u64 v[0:1], s[70:71], 0, v[0:1]
	s_mov_b64 s[2:3], 0x2000
	v_lshl_add_u64 v[34:35], v[0:1], 0, s[2:3]
	s_movk_i32 s2, 0x3000
	v_add_co_u32_e32 v36, vcc, s2, v0
	v_mbcnt_hi_u32_b32 v33, -1, v207
	s_nop 0
	v_addc_co_u32_e32 v37, vcc, 0, v1, vcc
	global_load_dwordx4 v[0:3], v[34:35], off offset:1024
	global_load_dwordx4 v[4:7], v[34:35], off offset:2048
	global_load_dwordx4 v[8:11], v[36:37], off offset:-4096
	global_load_dwordx4 v[12:15], v[34:35], off offset:3072
	global_load_dwordx4 v[16:19], v[36:37], off
	global_load_dwordx4 v[20:23], v[36:37], off offset:1024
	global_load_dwordx4 v[24:27], v[36:37], off offset:2048
	global_load_dwordx4 v[28:31], v[36:37], off offset:3072
	v_and_b32_e32 v34, 64, v33
	v_add_u32_e32 v34, 64, v34
	v_xor_b32_e32 v35, 32, v33
	v_cmp_lt_i32_e32 vcc, v35, v34
	v_ashrrev_i32_e32 v49, 31, v48
	v_and_b32_e32 v36, 63, v32
	v_cndmask_b32_e32 v35, v33, v35, vcc
	v_lshlrev_b32_e32 v54, 2, v35
	v_xor_b32_e32 v35, 16, v33
	v_cmp_lt_i32_e32 vcc, v35, v34
	s_mov_b64 s[2:3], 0x1000
	s_ashr_i32 s27, s26, 31
	v_cndmask_b32_e32 v35, v33, v35, vcc
	v_lshlrev_b32_e32 v55, 2, v35
	v_xor_b32_e32 v35, 8, v33
	v_cmp_lt_i32_e32 vcc, v35, v34
	s_mov_b64 s[6:7], 0x40c0000
	s_mov_b64 s[8:9], 0
	v_cndmask_b32_e32 v35, v33, v35, vcc
	v_lshlrev_b32_e32 v56, 2, v35
	v_xor_b32_e32 v35, 4, v33
	v_cmp_lt_i32_e32 vcc, v35, v34
	s_mov_b32 s10, 0x800000
	s_movk_i32 s11, 0x3fff
	v_cndmask_b32_e32 v35, v33, v35, vcc
	v_lshlrev_b32_e32 v57, 2, v35
	v_xor_b32_e32 v35, 2, v33
	v_cmp_lt_i32_e32 vcc, v35, v34
	s_nop 1
	v_cndmask_b32_e32 v35, v33, v35, vcc
	v_lshlrev_b32_e32 v58, 2, v35
	v_xor_b32_e32 v35, 1, v33
	v_cmp_lt_i32_e32 vcc, v35, v34
	s_nop 1
	v_cndmask_b32_e32 v33, v33, v35, vcc
	v_lshlrev_b64 v[34:35], 13, v[48:49]
	v_lshl_or_b32 v34, v36, 4, v34
	v_lshlrev_b32_e32 v59, 2, v33
	v_lshl_add_u64 v[32:33], s[20:21], 0, v[34:35]
	v_lshl_add_u64 v[50:51], v[32:33], 0, s[2:3]
	v_lshlrev_b64 v[32:33], 12, v[48:49]
	v_lshl_or_b32 v32, v36, 3, v32
	v_lshl_add_u64 v[32:33], s[22:23], 0, v[32:33]
	s_lshl_b64 s[2:3], s[26:27], 13
	v_lshl_add_u64 v[52:53], v[32:33], 0, s[6:7]
	s_lshl_b64 s[6:7], s[26:27], 12
	v_mov_b32_e32 v49, 0x358637bd
	global_load_dwordx4 v[100:103], v[50:51], off offset:-4096
	global_load_dwordx4 v[104:107], v[50:51], off offset:-3072
	global_load_dwordx4 v[108:111], v[50:51], off offset:-2048
	global_load_dwordx4 v[112:115], v[50:51], off offset:-1024
	global_load_dwordx4 v[116:119], v[50:51], off
	global_load_dwordx4 v[120:123], v[50:51], off offset:1024
	global_load_dwordx4 v[124:127], v[50:51], off offset:2048
	global_load_dwordx4 v[128:131], v[50:51], off offset:3072
	s_waitcnt vmcnt(0)
	s_branch .Lrn7_body

; DI int otid() { int t = threadIdx.x; asm volatile("" : "+v"(t)); return t; }
; DI void rmsnorm_phase(const float* __restrict__ X, const float* __restrict__ g, bf16_t* __restrict__ H, float* __restrict__ OF) {
;   const int tid = otid(), lane = tid & 63;
;   const int gw = blockIdx.x * NWV + (tid >> 6), nw = gridDim.x * NWV;
;   for (int row = gw; row < T; row += nw) {
;     const float* xr = X + (size_t)row * D;
;     f32x4 v[8];
;     float ss = 0.f;
; #pragma unroll
;     for (int i = 0; i < 8; ++i) { v[i] = *(const f32x4*)(xr + lane * 4 + 256 * i); ss += v[i][0] * v[i][0] + v[i][1] * v[i][1] + v[i][2] * v[i][2] + v[i][3] * v[i][3]; }
;     ss = wave_sum(ss);
;     const float rstd = rsqrtf(ss * (1.f / D) + EPS);
; #pragma unroll
;     for (int i = 0; i < 8; ++i) {
;       const f32x4 gg = *(const f32x4*)(g + lane * 4 + 256 * i);
.Lxr_1:
	s_movk_i32 s0, 0x4000
	v_cmp_gt_i32_e32 vcc, s0, v32
	s_and_saveexec_b64 s[0:1], vcc
	s_cbranch_execz .LBB0_1710
	v_lshlrev_b32_e32 v0, 4, v206
	v_and_b32_e32 v16, 0x3f0, v0
	v_mov_b32_e32 v17, 0
	v_lshl_add_u64 v[18:19], s[72:73], 0, v[16:17]
	s_movk_i32 s0, 0x1000
	v_add_co_u32_e32 v34, vcc, s0, v18
	global_load_dwordx4 v[0:3], v16, s[72:73]
	global_load_dwordx4 v[4:7], v16, s[72:73] offset:1024
	global_load_dwordx4 v[8:11], v16, s[72:73] offset:2048
	global_load_dwordx4 v[12:15], v16, s[72:73] offset:3072
	v_addc_co_u32_e32 v35, vcc, 0, v19, vcc
	global_load_dwordx4 v[16:19], v[34:35], off
	global_load_dwordx4 v[20:23], v[34:35], off offset:1024
	global_load_dwordx4 v[24:27], v[34:35], off offset:2048
	global_load_dwordx4 v[28:31], v[34:35], off offset:3072
	v_and_b32_e32 v33, 64, v198
	v_add_u32_e32 v33, 64, v33
	v_xor_b32_e32 v34, 32, v198
	v_cmp_lt_i32_e32 vcc, v34, v33
	s_mov_b64 s[0:1], 0x1000
	s_ashr_i32 s27, s26, 31
	v_cndmask_b32_e32 v34, v198, v34, vcc
	v_lshlrev_b32_e32 v36, 2, v34
	v_xor_b32_e32 v34, 16, v198
	v_cmp_lt_i32_e32 vcc, v34, v33
	s_lshl_b64 s[2:3], s[26:27], 13
	s_mov_b64 s[4:5], 0
	v_cndmask_b32_e32 v34, v198, v34, vcc
	v_lshlrev_b32_e32 v37, 2, v34
	v_xor_b32_e32 v34, 8, v198
	v_cmp_lt_i32_e32 vcc, v34, v33
	s_mov_b32 s6, 0x800000
	s_movk_i32 s7, 0x3fff
	v_cndmask_b32_e32 v34, v198, v34, vcc
	v_lshlrev_b32_e32 v38, 2, v34
	v_xor_b32_e32 v34, 4, v198
	v_cmp_lt_i32_e32 vcc, v34, v33
	s_nop 1
	v_cndmask_b32_e32 v34, v198, v34, vcc
	v_lshlrev_b32_e32 v39, 2, v34
	v_xor_b32_e32 v34, 2, v198
	v_cmp_lt_i32_e32 vcc, v34, v33
	s_nop 1
	v_cndmask_b32_e32 v34, v198, v34, vcc
	v_lshlrev_b32_e32 v40, 2, v34
	v_xor_b32_e32 v34, 1, v198
	v_cmp_lt_i32_e32 vcc, v34, v33
	s_nop 1
	v_cndmask_b32_e32 v33, v198, v34, vcc
	v_lshlrev_b32_e32 v41, 2, v33
	v_ashrrev_i32_e32 v33, 31, v32
	v_lshlrev_b64 v[34:35], 13, v[32:33]
	v_and_b32_e32 v33, 63, v206
	v_lshl_or_b32 v34, v33, 4, v34
	v_lshl_add_u64 v[34:35], s[20:21], 0, v[34:35]
	v_lshl_add_u64 v[34:35], v[34:35], 0, s[0:1]
	v_mov_b32_e32 v33, 0x358637bd
	global_load_dwordx4 v[100:103], v[34:35], off offset:-4096
	global_load_dwordx4 v[104:107], v[34:35], off offset:-3072
	global_load_dwordx4 v[108:111], v[34:35], off offset:-2048
	global_load_dwordx4 v[112:115], v[34:35], off offset:-1024
	global_load_dwordx4 v[116:119], v[34:35], off
	global_load_dwordx4 v[120:123], v[34:35], off offset:1024
	global_load_dwordx4 v[124:127], v[34:35], off offset:2048
	global_load_dwordx4 v[128:131], v[34:35], off offset:3072
	s_waitcnt vmcnt(0)
	s_branch .Lrn12_body
